# GEMM setprio flips kept; static prio raise for waves 0-3 applied from E4 (attention+GDN) entry only
# baseline (speedup 1.0000x reference)
; #define LAS __attribute__((address_space(3)))
; __global__ void __launch_bounds__(512, 2) mega_fwd(Params p) {
;     ...
;                     {
;                         PH_PTRS
;                         LAS int* qslot = (LAS int*)(lds + LDS_BYTES - 64);
;                         for (int rep = 0; rep <= PROBE_E4; ++rep) {
;                         int* ctr = (int*)(ctl + C_QCTR) + e * 64 + rep * 32;
;                         for (;;) {
;                             if (threadIdx.x == 0) *qslot = __hip_atomic_fetch_add(ctr, 1, __ATOMIC_RELAXED, __HIP_MEMORY_SCOPE_AGENT);
;                             __syncthreads();
;                             const int idx = *qslot;
;                             __syncthreads();
;                             if (idx >= 32 + 1024) break;
.LBB0_3622:
	s_movk_i32 s28, 0x90
	s_or_b64 exec, exec, s[0:1]
	s_mov_b64 s[0:1], s[92:93]
	v_readlane_b32 s4, v255, 23
	s_waitcnt lgkmcnt(0)
	s_barrier
	v_readlane_b32 s5, v255, 24
	s_add_u32 s4, s0, s4
	s_addc_u32 s5, s1, s5
	s_add_u32 s60, s4, 0x404000
	s_addc_u32 s61, s5, 0
	v_readfirstlane_b32 s29, v163
	s_lshr_b32 s29, s29, 6
	s_cmp_lt_u32 s29, 4
	s_cbranch_scc0 .Lprio_e4
	s_setprio 1
.Lprio_e4:
	s_getreg_b32 s100, hwreg(HW_REG_XCC_ID, 0, 4)
	s_and_b32 s100, s100, 7
	s_lshl_b32 s100, s100, 2
	s_mov_b32 s32, s60
	s_mov_b32 s75, s61
	s_mov_b32 s31, 0
	s_add_u32 s60, s32, s100
	s_addc_u32 s61, s75, 0
	s_add_u32 s62, s0, 0x11800000
	s_addc_u32 s63, s1, 0
	s_add_u32 s20, s0, 0x14800000
	s_addc_u32 s21, s1, 0
	s_add_u32 s64, s0, 0x17800000
	s_addc_u32 s65, s1, 0
	s_add_u32 s70, s0, 0xb800000
	s_addc_u32 s71, s1, 0
	s_add_u32 s72, s0, 0x19800000
	s_addc_u32 s73, s1, 0
	s_add_u32 s36, s0, 0x1b800000
	s_addc_u32 s37, s1, 0
	s_add_u32 s68, s0, 0x7800000
	s_addc_u32 s69, s1, 0
	s_add_u32 s84, s0, 0x9800000
	s_addc_u32 s85, s1, 0
	s_add_u32 s96, s0, 0x1fa00000
	s_addc_u32 s97, s1, 0
	s_add_u32 s58, s0, 0xf800000
	s_addc_u32 s59, s1, 0
	s_add_u32 s4, s0, 0x17810000
	s_addc_u32 s5, s1, 0
	s_mov_b32 s34, 0x2aaaaaab
	s_movk_i32 s35, 0xff
	s_branch .LBB0_3626
